# SSD conv item: the three previous-token loads issued together (single wait)
# baseline (speedup 1.0000x reference)
; DI float bf2f(bfr x) { return __uint_as_float(((unsigned)x) << 16); }
; DI void ssd_conv_phase(const Params& p, int ei, unsigned char* smem) {
;     ...
;     if (item < nconv) {
;       const int bc = item >> 4, slab = item & 15, c = slab * 64 + lane, tq = wave;
;       const int b = bc >> 7, chunk = bc & 127, t0l = chunk * 128 + tq * 32;
;       const size_t tg0 = (size_t)b * L + t0l;
;       const float w0 = cw[c], w1 = cw[1024 + c], w2 = cw[2048 + c], w3 = cw[3072 + c], bias = cb[c];
;       float r0 = (t0l >= 3) ? bf2f(xraw[(tg0 - 3) * 1024 + c]) : 0.f;
;       float r1 = (t0l >= 2) ? bf2f(xraw[(tg0 - 2) * 1024 + c]) : 0.f;
;       float r2 = (t0l >= 1) ? bf2f(xraw[(tg0 - 1) * 1024 + c]) : 0.f;
;       __syncthreads();
.LBB0_576:
	s_and_b64 vcc, exec, s[4:5]
	s_cbranch_vccz .LBB0_561
	s_and_b32 s24, s3, 15
	s_lshl_b32 s27, s24, 6
	v_or_b32_e32 v42, s27, v0
	v_lshlrev_b32_e32 v176, 2, v42
	v_lshl_add_u64 v[36:37], s[8:9], 0, v[176:177]
	s_movk_i32 s4, 0x1000
	v_add_co_u32_e32 v38, vcc, s4, v36
	v_readlane_b32 s4, v253, 55
	s_nop 0
	v_addc_co_u32_e32 v39, vcc, 0, v37, vcc
	v_add_co_u32_e32 v40, vcc, 0x2000, v36
	v_readlane_b32 s5, v253, 56
	s_nop 0
	v_addc_co_u32_e32 v41, vcc, 0, v37, vcc
	v_add_co_u32_e32 v36, vcc, 0x3000, v36
	global_load_dword v46, v176, s[8:9]
	global_load_dword v47, v[38:39], off
	global_load_dword v48, v[40:41], off
	v_addc_co_u32_e32 v37, vcc, 0, v37, vcc
	global_load_dword v49, v176, s[4:5]
	global_load_dword v50, v[36:37], off
	s_ashr_i32 s28, s3, 4
	s_lshl_b32 s4, s28, 7
	s_ashr_i32 s54, s3, 11
	s_and_b32 s4, s4, 0x3f80
	v_add_u32_e32 v38, s4, v4
	s_ashr_i32 s55, s54, 31
	s_lshl_b64 s[34:35], s[54:55], 14
	v_ashrrev_i32_e32 v39, 31, v38
	v_lshl_add_u64 v[36:37], s[34:35], 0, v[38:39]
	v_lshlrev_b64 v[36:37], 11, v[36:37]
	v_cmp_lt_i32_e32 vcc, 2, v38
	v_mov_b32_e32 v52, 0
	v_lshl_add_u64 v[36:37], s[62:63], 0, v[36:37]
	v_lshlrev_b32_e32 v176, 1, v42
	v_mov_b32_e32 v54, 0
	s_and_saveexec_b64 s[4:5], vcc
	s_cbranch_execz .LBB0_579
	v_lshl_add_u64 v[40:41], v[36:37], 0, v[176:177]
	v_add_co_u32_e32 v40, vcc, 0xfffff000, v40
	s_nop 1
	v_addc_co_u32_e32 v41, vcc, -1, v41, vcc
	global_load_ushort v54, v[40:41], off offset:-2048
.LBB0_579:
	s_or_b64 exec, exec, s[4:5]
	v_cmp_lt_i32_e32 vcc, 1, v38
	s_and_saveexec_b64 s[4:5], vcc
	s_cbranch_execz .LBB0_581
	v_lshl_add_u64 v[40:41], v[36:37], 0, v[176:177]
	global_load_ushort v52, v[40:41], off offset:-4096
.LBB0_581:
	s_or_b64 exec, exec, s[4:5]
	v_cmp_lt_i32_e32 vcc, 0, v38
	v_mov_b32_e32 v51, 0
	s_and_saveexec_b64 s[4:5], vcc
	s_cbranch_execz .LBB0_583
	v_lshl_add_u64 v[36:37], v[36:37], 0, v[176:177]
	global_load_ushort v51, v[36:37], off offset:-2048
.LBB0_583:
	s_or_b64 exec, exec, s[4:5]
	s_waitcnt vmcnt(0)
	v_lshlrev_b32_e32 v54, 16, v54
	v_lshlrev_b32_e32 v52, 16, v52
	v_lshlrev_b32_e32 v51, 16, v51
	s_and_b32 s4, s2, 15
	v_lshlrev_b32_e32 v36, 1, v0
	s_cmp_gt_u32 s24, 7
	v_lshl_or_b32 v176, s4, 7, v36
	s_cselect_b64 s[4:5], -1, 0
	s_cmp_lt_u32 s24, 12
	s_cselect_b64 s[24:25], -1, 0
	s_lshl_b32 s58, s3, 13
	s_lshl_b64 s[56:57], s[54:55], 24
	s_and_b32 s58, s58, 0xfe0000
	s_or_b32 s56, s56, s58
	v_lshl_add_u64 v[36:37], v[32:33], 0, s[56:57]
	s_lshl_b32 s56, s3, 14
	s_lshl_b64 s[54:55], s[54:55], 25
	s_and_b32 s56, s56, 0x1fc0000
	s_or_b32 s54, s54, s56
	v_lshl_add_u64 v[38:39], v[34:35], 0, s[54:55]
	s_lshl_b32 s54, s3, 3
	s_and_b32 s54, s54, 0x3f80
	s_add_u32 s34, s54, s34
	s_addc_u32 s35, 0, s35
	v_lshl_add_u64 v[42:43], s[34:35], 0, v[4:5]
	v_lshlrev_b64 v[40:41], 10, v[42:43]
	v_lshlrev_b64 v[42:43], 11, v[42:43]
	v_lshl_add_u64 v[40:41], s[6:7], 0, v[40:41]
	v_lshl_add_u64 v[42:43], s[62:63], 0, v[42:43]
	s_mov_b32 s34, 0
	s_barrier
	s_branch .LBB0_585
